# S5-out: second-round units split by row-block halves over XCD 0 and XCD 1 blocks (e-major in-chunk part)
# speedup vs baseline: 1.0004x; 1.0004x over previous
; __device__ __forceinline__ void ph_s5_out(Frame& F) {
;     ...
;     for (int u = F.vcu; u < 288; u += F.G) {
;         const int g = u / 9, nb = u % 9; int chunk = nb * 32 + r32; const bool valid = chunk < NCH; if (!valid) chunk = NCH - 1;
;         __syncthreads();
.LBB0_963:
	s_or_b64 exec, exec, s[24:25]
	s_cmp_lt_u32 s77, 64
	s_cbranch_scc0 .LBB0_977
	s_and_b32 s48, s77, 31
	s_addk_i32 s48, 0x100
	s_lshr_b32 s98, s77, 5
	s_lshl_b32 s99, s98, 5
	s_add_i32 s4, s4, s99
	s_branch .Lh_964

; #define GAS __attribute__((address_space(1)))
; #define LAS __attribute__((address_space(3)))
; __device__ __forceinline__ void ph_s5_out(Frame& F) {
;     ...
;         const LAS unsigned char* tl = L + ((63 + 2 * wave + (r32 >> 4)) * 16 + (r32 & 15)) * TP_PITCH + hh * 16;
; #pragma unroll 1
;         for (int s0 = 0; s0 < 64; s0 += 16) {
;             bf16x8_t bq[16];
; #pragma unroll
;             for (int e = 0; e < 16; ++e) bq[e] = *(const GAS bf16x8_t*)(ub + 512 * (s0 + e));
; #pragma unroll
;             for (int e = 0; e < 16; ++e) { const int sI = s0 + e; const bf16x8_t b = bq[e];
; #pragma unroll
;             for (int i = 0; i < 4; ++i) { const bf16x8_t a = *(const LAS bf16x8_t*)(tl + (16 * i - sI) * 16 * TP_PITCH); acc[i] = __builtin_amdgcn_mfma_f32_32x32x16_bf16(a, b, acc[i], 0, 0, 0); }
;             }
.Lh_972:
	s_mul_i32 s99, s98, 0x6000
	v_add_u32_e32 v226, s99, v91
	v_add_u32_e32 v68, 0xffff7000, v226
	ds_read_b128 v[84:87], v68 offset:11520
	ds_read_b128 v[96:99], v68 offset:23808
	ds_read_b128 v[100:103], v68 offset:36096
	ds_read_b128 v[104:107], v226 offset:11520
	ds_read_b128 v[108:111], v226 offset:23808
	ds_read_b128 v[120:123], v68 offset:10752
	ds_read_b128 v[124:127], v68 offset:23040
	ds_read_b128 v[128:131], v68 offset:35328
	ds_read_b128 v[132:135], v226 offset:10752
	ds_read_b128 v[136:139], v226 offset:23040
	s_waitcnt vmcnt(15) lgkmcnt(5)
	v_mfma_f32_32x32x16_bf16 v[50:65], v[104:107], v[142:145], v[50:65]
	v_mfma_f32_32x32x16_bf16 v[34:49], v[108:111], v[142:145], v[34:49]
	global_load_dwordx4 v[142:145], v[140:141], off
	s_waitcnt vmcnt(15)
	v_mfma_f32_32x32x16_bf16 v[50:65], v[100:103], v[146:149], v[50:65]
	v_mfma_f32_32x32x16_bf16 v[34:49], v[104:107], v[146:149], v[34:49]
	global_load_dwordx4 v[146:149], v[210:211], off
	s_waitcnt vmcnt(15)
	v_mfma_f32_32x32x16_bf16 v[50:65], v[96:99], v[150:153], v[50:65]
	v_mfma_f32_32x32x16_bf16 v[34:49], v[100:103], v[150:153], v[34:49]
	global_load_dwordx4 v[150:153], v[212:213], off
	s_waitcnt vmcnt(15)
	v_mfma_f32_32x32x16_bf16 v[50:65], v[84:87], v[154:157], v[50:65]
	v_mfma_f32_32x32x16_bf16 v[34:49], v[96:99], v[154:157], v[34:49]
	global_load_dwordx4 v[154:157], v[88:89], off
	ds_read_b128 v[84:87], v68 offset:9984
	ds_read_b128 v[96:99], v68 offset:22272
	ds_read_b128 v[100:103], v68 offset:34560
	ds_read_b128 v[104:107], v226 offset:9984
	ds_read_b128 v[108:111], v226 offset:22272
	s_waitcnt vmcnt(15) lgkmcnt(5)
	v_mfma_f32_32x32x16_bf16 v[50:65], v[132:135], v[158:161], v[50:65]
	v_mfma_f32_32x32x16_bf16 v[34:49], v[136:139], v[158:161], v[34:49]
	global_load_dwordx4 v[158:161], v[140:141], off offset:1024
	s_waitcnt vmcnt(15)
	v_mfma_f32_32x32x16_bf16 v[50:65], v[128:131], v[162:165], v[50:65]
	v_mfma_f32_32x32x16_bf16 v[34:49], v[132:135], v[162:165], v[34:49]
	global_load_dwordx4 v[162:165], v[210:211], off offset:1024
	s_waitcnt vmcnt(15)
	v_mfma_f32_32x32x16_bf16 v[50:65], v[124:127], v[166:169], v[50:65]
	v_mfma_f32_32x32x16_bf16 v[34:49], v[128:131], v[166:169], v[34:49]
	global_load_dwordx4 v[166:169], v[212:213], off offset:1024
	s_waitcnt vmcnt(15)
	v_mfma_f32_32x32x16_bf16 v[50:65], v[120:123], v[170:173], v[50:65]
	v_mfma_f32_32x32x16_bf16 v[34:49], v[124:127], v[170:173], v[34:49]
	global_load_dwordx4 v[170:173], v[88:89], off offset:1024
	ds_read_b128 v[120:123], v68 offset:9216
	ds_read_b128 v[124:127], v68 offset:21504
	ds_read_b128 v[128:131], v68 offset:33792
	ds_read_b128 v[132:135], v226 offset:9216
	ds_read_b128 v[136:139], v226 offset:21504
	s_waitcnt vmcnt(15) lgkmcnt(5)
	v_mfma_f32_32x32x16_bf16 v[50:65], v[104:107], v[174:177], v[50:65]
	v_mfma_f32_32x32x16_bf16 v[34:49], v[108:111], v[174:177], v[34:49]
	global_load_dwordx4 v[174:177], v[140:141], off offset:2048
	s_waitcnt vmcnt(15)
	v_mfma_f32_32x32x16_bf16 v[50:65], v[100:103], v[178:181], v[50:65]
	v_mfma_f32_32x32x16_bf16 v[34:49], v[104:107], v[178:181], v[34:49]
	global_load_dwordx4 v[178:181], v[210:211], off offset:2048
	s_waitcnt vmcnt(15)
	v_mfma_f32_32x32x16_bf16 v[50:65], v[96:99], v[182:185], v[50:65]
	v_mfma_f32_32x32x16_bf16 v[34:49], v[100:103], v[182:185], v[34:49]
	global_load_dwordx4 v[182:185], v[212:213], off offset:2048
	s_waitcnt vmcnt(15)
	v_mfma_f32_32x32x16_bf16 v[50:65], v[84:87], v[190:193], v[50:65]
	v_mfma_f32_32x32x16_bf16 v[34:49], v[96:99], v[190:193], v[34:49]
	global_load_dwordx4 v[190:193], v[88:89], off offset:2048
	ds_read_b128 v[84:87], v68 offset:8448
	ds_read_b128 v[96:99], v68 offset:20736
	ds_read_b128 v[100:103], v68 offset:33024
	ds_read_b128 v[104:107], v226 offset:8448
	ds_read_b128 v[108:111], v226 offset:20736
	s_waitcnt vmcnt(15) lgkmcnt(5)
	v_mfma_f32_32x32x16_bf16 v[50:65], v[132:135], v[194:197], v[50:65]
	v_mfma_f32_32x32x16_bf16 v[34:49], v[136:139], v[194:197], v[34:49]
	global_load_dwordx4 v[194:197], v[140:141], off offset:3072
	s_waitcnt vmcnt(15)
	v_mfma_f32_32x32x16_bf16 v[50:65], v[128:131], v[198:201], v[50:65]
	v_mfma_f32_32x32x16_bf16 v[34:49], v[132:135], v[198:201], v[34:49]
	global_load_dwordx4 v[198:201], v[210:211], off offset:3072
	s_waitcnt vmcnt(15)
	v_mfma_f32_32x32x16_bf16 v[50:65], v[124:127], v[202:205], v[50:65]
	v_mfma_f32_32x32x16_bf16 v[34:49], v[128:131], v[202:205], v[34:49]
	global_load_dwordx4 v[202:205], v[212:213], off offset:3072
	s_waitcnt vmcnt(15)
	v_mfma_f32_32x32x16_bf16 v[50:65], v[120:123], v[206:209], v[50:65]
	v_mfma_f32_32x32x16_bf16 v[34:49], v[124:127], v[206:209], v[34:49]
	global_load_dwordx4 v[206:209], v[88:89], off offset:3072
	v_lshl_add_u64 v[140:141], v[140:141], 0, s[20:21]
	v_lshl_add_u64 v[210:211], v[210:211], 0, s[20:21]
	v_lshl_add_u64 v[212:213], v[212:213], 0, s[20:21]
	v_lshl_add_u64 v[88:89], v[88:89], 0, s[20:21]
	ds_read_b128 v[120:123], v68 offset:7680
	ds_read_b128 v[124:127], v68 offset:19968
	ds_read_b128 v[128:131], v68 offset:32256
	ds_read_b128 v[132:135], v226 offset:7680
	ds_read_b128 v[136:139], v226 offset:19968
	s_waitcnt vmcnt(15) lgkmcnt(5)
	v_mfma_f32_32x32x16_bf16 v[50:65], v[104:107], v[142:145], v[50:65]
	v_mfma_f32_32x32x16_bf16 v[34:49], v[108:111], v[142:145], v[34:49]
	global_load_dwordx4 v[142:145], v[140:141], off offset:-4096
	s_waitcnt vmcnt(15)
	v_mfma_f32_32x32x16_bf16 v[50:65], v[100:103], v[146:149], v[50:65]
	v_mfma_f32_32x32x16_bf16 v[34:49], v[104:107], v[146:149], v[34:49]
	global_load_dwordx4 v[146:149], v[210:211], off offset:-4096
	s_waitcnt vmcnt(15)
; #define GAS __attribute__((address_space(1)))
; #define LAS __attribute__((address_space(3)))
; __device__ __forceinline__ void ph_s5_out(Frame& F) {
;     ...
;         const LAS unsigned char* tl = L + ((63 + 2 * wave + (r32 >> 4)) * 16 + (r32 & 15)) * TP_PITCH + hh * 16;
; #pragma unroll 1
;         for (int s0 = 0; s0 < 64; s0 += 16) {
;             bf16x8_t bq[16];
; #pragma unroll
;             for (int e = 0; e < 16; ++e) bq[e] = *(const GAS bf16x8_t*)(ub + 512 * (s0 + e));
; #pragma unroll
;             for (int e = 0; e < 16; ++e) { const int sI = s0 + e; const bf16x8_t b = bq[e];
; #pragma unroll
;             for (int i = 0; i < 4; ++i) { const bf16x8_t a = *(const LAS bf16x8_t*)(tl + (16 * i - sI) * 16 * TP_PITCH); acc[i] = __builtin_amdgcn_mfma_f32_32x32x16_bf16(a, b, acc[i], 0, 0, 0); }
;             }
	v_mfma_f32_32x32x16_bf16 v[50:65], v[96:99], v[150:153], v[50:65]
	v_mfma_f32_32x32x16_bf16 v[34:49], v[100:103], v[150:153], v[34:49]
	global_load_dwordx4 v[150:153], v[212:213], off offset:-4096
	s_waitcnt vmcnt(15)
	v_mfma_f32_32x32x16_bf16 v[50:65], v[84:87], v[154:157], v[50:65]
	v_mfma_f32_32x32x16_bf16 v[34:49], v[96:99], v[154:157], v[34:49]
	global_load_dwordx4 v[154:157], v[88:89], off offset:-4096
	ds_read_b128 v[84:87], v68 offset:6912
	ds_read_b128 v[96:99], v68 offset:19200
	ds_read_b128 v[100:103], v68 offset:31488
	ds_read_b128 v[104:107], v226 offset:6912
	ds_read_b128 v[108:111], v226 offset:19200
	s_waitcnt vmcnt(15) lgkmcnt(5)
	v_mfma_f32_32x32x16_bf16 v[50:65], v[132:135], v[158:161], v[50:65]
	v_mfma_f32_32x32x16_bf16 v[34:49], v[136:139], v[158:161], v[34:49]
	global_load_dwordx4 v[158:161], v[140:141], off offset:-3072
	s_waitcnt vmcnt(15)
	v_mfma_f32_32x32x16_bf16 v[50:65], v[128:131], v[162:165], v[50:65]
	v_mfma_f32_32x32x16_bf16 v[34:49], v[132:135], v[162:165], v[34:49]
	global_load_dwordx4 v[162:165], v[210:211], off offset:-3072
	s_waitcnt vmcnt(15)
	v_mfma_f32_32x32x16_bf16 v[50:65], v[124:127], v[166:169], v[50:65]
	v_mfma_f32_32x32x16_bf16 v[34:49], v[128:131], v[166:169], v[34:49]
	global_load_dwordx4 v[166:169], v[212:213], off offset:-3072
	s_waitcnt vmcnt(15)
	v_mfma_f32_32x32x16_bf16 v[50:65], v[120:123], v[170:173], v[50:65]
	v_mfma_f32_32x32x16_bf16 v[34:49], v[124:127], v[170:173], v[34:49]
	global_load_dwordx4 v[170:173], v[88:89], off offset:-3072
	ds_read_b128 v[120:123], v68 offset:6144
	ds_read_b128 v[124:127], v68 offset:18432
	ds_read_b128 v[128:131], v68 offset:30720
	ds_read_b128 v[132:135], v226 offset:6144
	ds_read_b128 v[136:139], v226 offset:18432
	s_waitcnt vmcnt(15) lgkmcnt(5)
	v_mfma_f32_32x32x16_bf16 v[50:65], v[104:107], v[174:177], v[50:65]
	v_mfma_f32_32x32x16_bf16 v[34:49], v[108:111], v[174:177], v[34:49]
	global_load_dwordx4 v[174:177], v[140:141], off offset:-2048
	s_waitcnt vmcnt(15)
	v_mfma_f32_32x32x16_bf16 v[50:65], v[100:103], v[178:181], v[50:65]
	v_mfma_f32_32x32x16_bf16 v[34:49], v[104:107], v[178:181], v[34:49]
	global_load_dwordx4 v[178:181], v[210:211], off offset:-2048
	s_waitcnt vmcnt(15)
	v_mfma_f32_32x32x16_bf16 v[50:65], v[96:99], v[182:185], v[50:65]
	v_mfma_f32_32x32x16_bf16 v[34:49], v[100:103], v[182:185], v[34:49]
	global_load_dwordx4 v[182:185], v[212:213], off offset:-2048
	s_waitcnt vmcnt(15)
	v_mfma_f32_32x32x16_bf16 v[50:65], v[84:87], v[190:193], v[50:65]
	v_mfma_f32_32x32x16_bf16 v[34:49], v[96:99], v[190:193], v[34:49]
	global_load_dwordx4 v[190:193], v[88:89], off offset:-2048
	ds_read_b128 v[84:87], v68 offset:5376
	ds_read_b128 v[96:99], v68 offset:17664
	ds_read_b128 v[100:103], v68 offset:29952
	ds_read_b128 v[104:107], v226 offset:5376
	ds_read_b128 v[108:111], v226 offset:17664
	s_waitcnt vmcnt(15) lgkmcnt(5)
	v_mfma_f32_32x32x16_bf16 v[50:65], v[132:135], v[194:197], v[50:65]
	v_mfma_f32_32x32x16_bf16 v[34:49], v[136:139], v[194:197], v[34:49]
	global_load_dwordx4 v[194:197], v[140:141], off offset:-1024
	s_waitcnt vmcnt(15)
	v_mfma_f32_32x32x16_bf16 v[50:65], v[128:131], v[198:201], v[50:65]
	v_mfma_f32_32x32x16_bf16 v[34:49], v[132:135], v[198:201], v[34:49]
	global_load_dwordx4 v[198:201], v[210:211], off offset:-1024
	s_waitcnt vmcnt(15)
	v_mfma_f32_32x32x16_bf16 v[50:65], v[124:127], v[202:205], v[50:65]
	v_mfma_f32_32x32x16_bf16 v[34:49], v[128:131], v[202:205], v[34:49]
	global_load_dwordx4 v[202:205], v[212:213], off offset:-1024
	s_waitcnt vmcnt(15)
	v_mfma_f32_32x32x16_bf16 v[50:65], v[120:123], v[206:209], v[50:65]
	v_mfma_f32_32x32x16_bf16 v[34:49], v[124:127], v[206:209], v[34:49]
	global_load_dwordx4 v[206:209], v[88:89], off offset:-1024
	ds_read_b128 v[120:123], v68 offset:4608
	ds_read_b128 v[124:127], v68 offset:16896
	ds_read_b128 v[128:131], v68 offset:29184
	ds_read_b128 v[132:135], v226 offset:4608
	ds_read_b128 v[136:139], v226 offset:16896
	s_waitcnt vmcnt(15) lgkmcnt(5)
	v_mfma_f32_32x32x16_bf16 v[50:65], v[104:107], v[142:145], v[50:65]
	v_mfma_f32_32x32x16_bf16 v[34:49], v[108:111], v[142:145], v[34:49]
	global_load_dwordx4 v[142:145], v[140:141], off
	s_waitcnt vmcnt(15)
	v_mfma_f32_32x32x16_bf16 v[50:65], v[100:103], v[146:149], v[50:65]
	v_mfma_f32_32x32x16_bf16 v[34:49], v[104:107], v[146:149], v[34:49]
	global_load_dwordx4 v[146:149], v[210:211], off
	s_waitcnt vmcnt(15)
	v_mfma_f32_32x32x16_bf16 v[50:65], v[96:99], v[150:153], v[50:65]
	v_mfma_f32_32x32x16_bf16 v[34:49], v[100:103], v[150:153], v[34:49]
	global_load_dwordx4 v[150:153], v[212:213], off
	s_waitcnt vmcnt(15)
	v_mfma_f32_32x32x16_bf16 v[50:65], v[84:87], v[154:157], v[50:65]
	v_mfma_f32_32x32x16_bf16 v[34:49], v[96:99], v[154:157], v[34:49]
	global_load_dwordx4 v[154:157], v[88:89], off
	ds_read_b128 v[84:87], v68 offset:3840
	ds_read_b128 v[96:99], v68 offset:16128
	ds_read_b128 v[100:103], v68 offset:28416
	ds_read_b128 v[104:107], v226 offset:3840
	ds_read_b128 v[108:111], v226 offset:16128
	s_waitcnt vmcnt(15) lgkmcnt(5)
	v_mfma_f32_32x32x16_bf16 v[50:65], v[132:135], v[158:161], v[50:65]
	v_mfma_f32_32x32x16_bf16 v[34:49], v[136:139], v[158:161], v[34:49]
	global_load_dwordx4 v[158:161], v[140:141], off offset:1024
	s_waitcnt vmcnt(15)
	v_mfma_f32_32x32x16_bf16 v[50:65], v[128:131], v[162:165], v[50:65]
	v_mfma_f32_32x32x16_bf16 v[34:49], v[132:135], v[162:165], v[34:49]
	global_load_dwordx4 v[162:165], v[210:211], off offset:1024
	s_waitcnt vmcnt(15)
	v_mfma_f32_32x32x16_bf16 v[50:65], v[124:127], v[166:169], v[50:65]
	v_mfma_f32_32x32x16_bf16 v[34:49], v[128:131], v[166:169], v[34:49]
	global_load_dwordx4 v[166:169], v[212:213], off offset:1024
	s_waitcnt vmcnt(15)
; #define GAS __attribute__((address_space(1)))
; #define LAS __attribute__((address_space(3)))
; __device__ __forceinline__ void ph_s5_out(Frame& F) {
;     ...
;         for (int s0 = 0; s0 < 64; s0 += 16) {
;             bf16x8_t bq[16];
; #pragma unroll
;             for (int e = 0; e < 16; ++e) bq[e] = *(const GAS bf16x8_t*)(ub + 512 * (s0 + e));
; #pragma unroll
;             for (int e = 0; e < 16; ++e) { const int sI = s0 + e; const bf16x8_t b = bq[e];
; #pragma unroll
;             for (int i = 0; i < 4; ++i) { const bf16x8_t a = *(const LAS bf16x8_t*)(tl + (16 * i - sI) * 16 * TP_PITCH); acc[i] = __builtin_amdgcn_mfma_f32_32x32x16_bf16(a, b, acc[i], 0, 0, 0); }
;             }
;         }
;         { const bf16* sb = (const bf16*)(ws + WS_SIN) + (size_t)g * 9 * 16 * 512 + ((size_t)nb * 16 * 64 + lane) * 8;
;           const bf16* wc = (const bf16*)(ws + WS_WC) + (size_t)g * 1024 * 256 + (((size_t)wave * 16) * 64 + lane) * 8;
; #pragma unroll 4
;           for (int kk = 0; kk < 16; ++kk) {
;               const bf16x8_t b = *(const GAS bf16x8_t*)(sb + 512 * kk);
; #pragma unroll
;               for (int i = 0; i < 4; ++i) { const bf16x8_t a = *(const GAS bf16x8_t*)(wc + (size_t)(8 * i) * 16 * 512 + 512 * kk); acc[i] = __builtin_amdgcn_mfma_f32_32x32x16_bf16(a, b, acc[i], 0, 0, 0); }
;           } }
	v_mfma_f32_32x32x16_bf16 v[50:65], v[120:123], v[170:173], v[50:65]
	v_mfma_f32_32x32x16_bf16 v[34:49], v[124:127], v[170:173], v[34:49]
	global_load_dwordx4 v[170:173], v[88:89], off offset:1024
	ds_read_b128 v[120:123], v68 offset:3072
	ds_read_b128 v[124:127], v68 offset:15360
	ds_read_b128 v[128:131], v68 offset:27648
	ds_read_b128 v[132:135], v226 offset:3072
	ds_read_b128 v[136:139], v226 offset:15360
	s_waitcnt vmcnt(15) lgkmcnt(5)
	v_mfma_f32_32x32x16_bf16 v[50:65], v[104:107], v[174:177], v[50:65]
	v_mfma_f32_32x32x16_bf16 v[34:49], v[108:111], v[174:177], v[34:49]
	global_load_dwordx4 v[174:177], v[140:141], off offset:2048
	s_waitcnt vmcnt(15)
	v_mfma_f32_32x32x16_bf16 v[50:65], v[100:103], v[178:181], v[50:65]
	v_mfma_f32_32x32x16_bf16 v[34:49], v[104:107], v[178:181], v[34:49]
	global_load_dwordx4 v[178:181], v[210:211], off offset:2048
	s_waitcnt vmcnt(15)
	v_mfma_f32_32x32x16_bf16 v[50:65], v[96:99], v[182:185], v[50:65]
	v_mfma_f32_32x32x16_bf16 v[34:49], v[100:103], v[182:185], v[34:49]
	global_load_dwordx4 v[182:185], v[212:213], off offset:2048
	s_waitcnt vmcnt(15)
	v_mfma_f32_32x32x16_bf16 v[50:65], v[84:87], v[190:193], v[50:65]
	v_mfma_f32_32x32x16_bf16 v[34:49], v[96:99], v[190:193], v[34:49]
	global_load_dwordx4 v[190:193], v[88:89], off offset:2048
	ds_read_b128 v[84:87], v68 offset:2304
	ds_read_b128 v[96:99], v68 offset:14592
	ds_read_b128 v[100:103], v68 offset:26880
	ds_read_b128 v[104:107], v226 offset:2304
	ds_read_b128 v[108:111], v226 offset:14592
	s_waitcnt vmcnt(15) lgkmcnt(5)
	v_mfma_f32_32x32x16_bf16 v[50:65], v[132:135], v[194:197], v[50:65]
	v_mfma_f32_32x32x16_bf16 v[34:49], v[136:139], v[194:197], v[34:49]
	global_load_dwordx4 v[194:197], v[140:141], off offset:3072
	s_waitcnt vmcnt(15)
	v_mfma_f32_32x32x16_bf16 v[50:65], v[128:131], v[198:201], v[50:65]
	v_mfma_f32_32x32x16_bf16 v[34:49], v[132:135], v[198:201], v[34:49]
	global_load_dwordx4 v[198:201], v[210:211], off offset:3072
	s_waitcnt vmcnt(15)
	v_mfma_f32_32x32x16_bf16 v[50:65], v[124:127], v[202:205], v[50:65]
	v_mfma_f32_32x32x16_bf16 v[34:49], v[128:131], v[202:205], v[34:49]
	global_load_dwordx4 v[202:205], v[212:213], off offset:3072
	s_waitcnt vmcnt(15)
	v_mfma_f32_32x32x16_bf16 v[50:65], v[120:123], v[206:209], v[50:65]
	v_mfma_f32_32x32x16_bf16 v[34:49], v[124:127], v[206:209], v[34:49]
	global_load_dwordx4 v[206:209], v[88:89], off offset:3072
	s_ashr_i32 s25, s24, 31
	s_mul_i32 s49, s26, 0x24000
	s_lshl_b64 s[28:29], s[24:25], 14
	s_lshl_b64 s[34:35], s[26:27], 19
	s_mul_hi_i32 s31, s26, 0x24000
	s_add_u32 s28, s49, s28
	s_addc_u32 s29, s31, s29
	s_add_u32 s28, s28, 0x800
	s_addc_u32 s29, s29, 0
	s_add_u32 s34, s34, 0x9901000
	s_addc_u32 s35, s35, 0
	v_lshl_add_u64 v[88:89], v[80:81], 0, s[28:29]
	v_lshl_add_u64 v[214:215], v[78:79], 0, s[34:35]
	s_mov_b64 s[28:29], 0x20000
	v_lshl_add_u64 v[216:217], v[214:215], 0, s[28:29]
	v_lshl_add_u64 v[140:141], v[216:217], 0, s[28:29]
	v_lshl_add_u64 v[186:187], v[140:141], 0, s[28:29]
	s_lshl_b32 s28, s98, 18
	s_mov_b32 s29, 0
	v_lshl_add_u64 v[214:215], v[214:215], 0, s[28:29]
	v_lshl_add_u64 v[216:217], v[216:217], 0, s[28:29]
	ds_read_b128 v[120:123], v68 offset:1536
	ds_read_b128 v[124:127], v68 offset:13824
	ds_read_b128 v[128:131], v68 offset:26112
	ds_read_b128 v[132:135], v226 offset:1536
	ds_read_b128 v[136:139], v226 offset:13824
	s_waitcnt vmcnt(15) lgkmcnt(5)
	v_mfma_f32_32x32x16_bf16 v[50:65], v[104:107], v[142:145], v[50:65]
	v_mfma_f32_32x32x16_bf16 v[34:49], v[108:111], v[142:145], v[34:49]
	global_load_dwordx4 v[142:145], v[88:89], off offset:-4096
	s_waitcnt vmcnt(15)
	v_mfma_f32_32x32x16_bf16 v[50:65], v[100:103], v[146:149], v[50:65]
	v_mfma_f32_32x32x16_bf16 v[34:49], v[104:107], v[146:149], v[34:49]
	global_load_dwordx4 v[146:149], v[214:215], off offset:-4096
	s_waitcnt vmcnt(15)
	v_mfma_f32_32x32x16_bf16 v[50:65], v[96:99], v[150:153], v[50:65]
	v_mfma_f32_32x32x16_bf16 v[34:49], v[100:103], v[150:153], v[34:49]
	global_load_dwordx4 v[150:153], v[216:217], off offset:-4096
	s_waitcnt vmcnt(15)
	v_mfma_f32_32x32x16_bf16 v[50:65], v[84:87], v[154:157], v[50:65]
	v_mfma_f32_32x32x16_bf16 v[34:49], v[96:99], v[154:157], v[34:49]
	global_load_dwordx4 v[154:157], v[88:89], off offset:-3072
	ds_read_b128 v[84:87], v68 offset:768
	ds_read_b128 v[96:99], v68 offset:13056
	ds_read_b128 v[100:103], v68 offset:25344
	ds_read_b128 v[104:107], v226 offset:768
	ds_read_b128 v[108:111], v226 offset:13056
	s_waitcnt vmcnt(15) lgkmcnt(5)
	v_mfma_f32_32x32x16_bf16 v[50:65], v[132:135], v[158:161], v[50:65]
	v_mfma_f32_32x32x16_bf16 v[34:49], v[136:139], v[158:161], v[34:49]
	global_load_dwordx4 v[158:161], v[214:215], off offset:-3072
	s_waitcnt vmcnt(15)
	v_mfma_f32_32x32x16_bf16 v[50:65], v[128:131], v[162:165], v[50:65]
	v_mfma_f32_32x32x16_bf16 v[34:49], v[132:135], v[162:165], v[34:49]
	global_load_dwordx4 v[162:165], v[216:217], off offset:-3072
	s_waitcnt vmcnt(15)
	v_mfma_f32_32x32x16_bf16 v[50:65], v[124:127], v[166:169], v[50:65]
	v_mfma_f32_32x32x16_bf16 v[34:49], v[128:131], v[166:169], v[34:49]
	global_load_dwordx4 v[166:169], v[88:89], off offset:-2048
	s_waitcnt vmcnt(15)
	v_mfma_f32_32x32x16_bf16 v[50:65], v[120:123], v[170:173], v[50:65]
	v_mfma_f32_32x32x16_bf16 v[34:49], v[124:127], v[170:173], v[34:49]
	global_load_dwordx4 v[170:173], v[214:215], off offset:-2048
	ds_read_b128 v[120:123], v68 offset:0
	ds_read_b128 v[124:127], v68 offset:12288
	ds_read_b128 v[128:131], v68 offset:24576
	ds_read_b128 v[132:135], v226 offset:0
	ds_read_b128 v[136:139], v226 offset:12288
	s_waitcnt vmcnt(15) lgkmcnt(5)
; #define GAS __attribute__((address_space(1)))
; #define LAS __attribute__((address_space(3)))
; __device__ __forceinline__ void ph_s5_out(Frame& F) {
;     ...
;             for (int i = 0; i < 4; ++i) { const bf16x8_t a = *(const LAS bf16x8_t*)(tl + (16 * i - sI) * 16 * TP_PITCH); acc[i] = __builtin_amdgcn_mfma_f32_32x32x16_bf16(a, b, acc[i], 0, 0, 0); }
;             }
;         }
;         { const bf16* sb = (const bf16*)(ws + WS_SIN) + (size_t)g * 9 * 16 * 512 + ((size_t)nb * 16 * 64 + lane) * 8;
;           const bf16* wc = (const bf16*)(ws + WS_WC) + (size_t)g * 1024 * 256 + (((size_t)wave * 16) * 64 + lane) * 8;
; #pragma unroll 4
;           for (int kk = 0; kk < 16; ++kk) {
;               const bf16x8_t b = *(const GAS bf16x8_t*)(sb + 512 * kk);
; #pragma unroll
;               for (int i = 0; i < 4; ++i) { const bf16x8_t a = *(const GAS bf16x8_t*)(wc + (size_t)(8 * i) * 16 * 512 + 512 * kk); acc[i] = __builtin_amdgcn_mfma_f32_32x32x16_bf16(a, b, acc[i], 0, 0, 0); }
;           } }
;         if (valid) {
	v_mfma_f32_32x32x16_bf16 v[50:65], v[104:107], v[174:177], v[50:65]
	v_mfma_f32_32x32x16_bf16 v[34:49], v[108:111], v[174:177], v[34:49]
	global_load_dwordx4 v[174:177], v[216:217], off offset:-2048
	s_waitcnt vmcnt(15)
	v_mfma_f32_32x32x16_bf16 v[50:65], v[100:103], v[178:181], v[50:65]
	v_mfma_f32_32x32x16_bf16 v[34:49], v[104:107], v[178:181], v[34:49]
	global_load_dwordx4 v[178:181], v[88:89], off offset:-1024
	s_waitcnt vmcnt(15)
	v_mfma_f32_32x32x16_bf16 v[50:65], v[96:99], v[182:185], v[50:65]
	v_mfma_f32_32x32x16_bf16 v[34:49], v[100:103], v[182:185], v[34:49]
	global_load_dwordx4 v[182:185], v[214:215], off offset:-1024
	s_waitcnt vmcnt(15)
	v_mfma_f32_32x32x16_bf16 v[50:65], v[84:87], v[190:193], v[50:65]
	v_mfma_f32_32x32x16_bf16 v[34:49], v[96:99], v[190:193], v[34:49]
	global_load_dwordx4 v[190:193], v[216:217], off offset:-1024
	s_waitcnt vmcnt(15) lgkmcnt(0)
	v_mfma_f32_32x32x16_bf16 v[50:65], v[132:135], v[194:197], v[50:65]
	v_mfma_f32_32x32x16_bf16 v[34:49], v[136:139], v[194:197], v[34:49]
	global_load_dwordx4 v[194:197], v[88:89], off
	s_waitcnt vmcnt(15)
	v_mfma_f32_32x32x16_bf16 v[50:65], v[128:131], v[198:201], v[50:65]
	v_mfma_f32_32x32x16_bf16 v[34:49], v[132:135], v[198:201], v[34:49]
	global_load_dwordx4 v[198:201], v[214:215], off
	s_waitcnt vmcnt(15)
	v_mfma_f32_32x32x16_bf16 v[50:65], v[124:127], v[202:205], v[50:65]
	v_mfma_f32_32x32x16_bf16 v[34:49], v[128:131], v[202:205], v[34:49]
	global_load_dwordx4 v[202:205], v[216:217], off
	s_waitcnt vmcnt(15)
	v_mfma_f32_32x32x16_bf16 v[50:65], v[120:123], v[206:209], v[50:65]
	v_mfma_f32_32x32x16_bf16 v[34:49], v[124:127], v[206:209], v[34:49]
	global_load_dwordx4 v[206:209], v[88:89], off offset:1024
	global_load_dwordx4 v[96:99], v[214:215], off offset:1024
	global_load_dwordx4 v[100:103], v[216:217], off offset:1024
	global_load_dwordx4 v[104:107], v[88:89], off offset:2048
	global_load_dwordx4 v[108:111], v[214:215], off offset:2048
	global_load_dwordx4 v[112:115], v[216:217], off offset:2048
	global_load_dwordx4 v[116:119], v[88:89], off offset:3072
	global_load_dwordx4 v[120:123], v[214:215], off offset:3072
	global_load_dwordx4 v[124:127], v[216:217], off offset:3072
	v_lshl_add_u64 v[88:89], v[88:89], 0, s[20:21]
	v_lshl_add_u64 v[214:215], v[214:215], 0, s[20:21]
	v_lshl_add_u64 v[216:217], v[216:217], 0, s[20:21]
	global_load_dwordx4 v[128:131], v[88:89], off offset:-4096
	global_load_dwordx4 v[132:135], v[214:215], off offset:-4096
	global_load_dwordx4 v[136:139], v[216:217], off offset:-4096
	s_waitcnt vmcnt(25)
	v_mfma_f32_32x32x16_bf16 v[50:65], v[146:149], v[142:145], v[50:65]
	global_load_dwordx4 v[146:149], v[88:89], off offset:-3072
	s_waitcnt vmcnt(25)
	v_mfma_f32_32x32x16_bf16 v[34:49], v[150:153], v[142:145], v[34:49]
	global_load_dwordx4 v[150:153], v[214:215], off offset:-3072
	global_load_dwordx4 v[142:145], v[216:217], off offset:-3072
	s_waitcnt vmcnt(25)
	v_mfma_f32_32x32x16_bf16 v[50:65], v[158:161], v[154:157], v[50:65]
	global_load_dwordx4 v[158:161], v[88:89], off offset:-2048
	s_waitcnt vmcnt(25)
	v_mfma_f32_32x32x16_bf16 v[34:49], v[162:165], v[154:157], v[34:49]
	global_load_dwordx4 v[162:165], v[214:215], off offset:-2048
	global_load_dwordx4 v[154:157], v[216:217], off offset:-2048
	s_waitcnt vmcnt(25)
	v_mfma_f32_32x32x16_bf16 v[50:65], v[170:173], v[166:169], v[50:65]
	global_load_dwordx4 v[170:173], v[88:89], off offset:-1024
	s_waitcnt vmcnt(25)
	v_mfma_f32_32x32x16_bf16 v[34:49], v[174:177], v[166:169], v[34:49]
	global_load_dwordx4 v[174:177], v[214:215], off offset:-1024
	global_load_dwordx4 v[166:169], v[216:217], off offset:-1024
	s_waitcnt vmcnt(25)
	v_mfma_f32_32x32x16_bf16 v[50:65], v[182:185], v[178:181], v[50:65]
	global_load_dwordx4 v[182:185], v[88:89], off
	s_waitcnt vmcnt(25)
	v_mfma_f32_32x32x16_bf16 v[34:49], v[190:193], v[178:181], v[34:49]
	global_load_dwordx4 v[190:193], v[214:215], off
	global_load_dwordx4 v[178:181], v[216:217], off
	s_waitcnt vmcnt(25)
	v_mfma_f32_32x32x16_bf16 v[50:65], v[198:201], v[194:197], v[50:65]
	global_load_dwordx4 v[198:201], v[88:89], off offset:1024
	s_waitcnt vmcnt(25)
	v_mfma_f32_32x32x16_bf16 v[34:49], v[202:205], v[194:197], v[34:49]
	global_load_dwordx4 v[202:205], v[214:215], off offset:1024
	global_load_dwordx4 v[194:197], v[216:217], off offset:1024
	s_waitcnt vmcnt(25)
	v_mfma_f32_32x32x16_bf16 v[50:65], v[96:99], v[206:209], v[50:65]
	global_load_dwordx4 v[96:99], v[88:89], off offset:2048
	s_waitcnt vmcnt(25)
	v_mfma_f32_32x32x16_bf16 v[34:49], v[100:103], v[206:209], v[34:49]
	global_load_dwordx4 v[100:103], v[214:215], off offset:2048
	global_load_dwordx4 v[206:209], v[216:217], off offset:2048
	s_waitcnt vmcnt(25)
	v_mfma_f32_32x32x16_bf16 v[50:65], v[108:111], v[104:107], v[50:65]
	global_load_dwordx4 v[108:111], v[88:89], off offset:3072
	s_waitcnt vmcnt(25)
	v_mfma_f32_32x32x16_bf16 v[34:49], v[112:115], v[104:107], v[34:49]
	global_load_dwordx4 v[112:115], v[214:215], off offset:3072
	global_load_dwordx4 v[104:107], v[216:217], off offset:3072
	s_waitcnt vmcnt(25)
	v_mfma_f32_32x32x16_bf16 v[50:65], v[120:123], v[116:119], v[50:65]
	s_waitcnt vmcnt(24)
	v_mfma_f32_32x32x16_bf16 v[34:49], v[124:127], v[116:119], v[34:49]
	s_waitcnt vmcnt(22)
	v_mfma_f32_32x32x16_bf16 v[50:65], v[132:135], v[128:131], v[50:65]
	s_waitcnt vmcnt(21)
	v_mfma_f32_32x32x16_bf16 v[34:49], v[136:139], v[128:131], v[34:49]
	s_waitcnt vmcnt(19)
	v_mfma_f32_32x32x16_bf16 v[50:65], v[150:153], v[146:149], v[50:65]
	s_waitcnt vmcnt(18)
	v_mfma_f32_32x32x16_bf16 v[34:49], v[142:145], v[146:149], v[34:49]
	s_waitcnt vmcnt(16)
	v_mfma_f32_32x32x16_bf16 v[50:65], v[162:165], v[158:161], v[50:65]
	s_waitcnt vmcnt(15)
	v_mfma_f32_32x32x16_bf16 v[34:49], v[154:157], v[158:161], v[34:49]
	s_waitcnt vmcnt(13)
	v_mfma_f32_32x32x16_bf16 v[50:65], v[174:177], v[170:173], v[50:65]
	s_waitcnt vmcnt(12)
	v_mfma_f32_32x32x16_bf16 v[34:49], v[166:169], v[170:173], v[34:49]
	s_waitcnt vmcnt(10)
	v_mfma_f32_32x32x16_bf16 v[50:65], v[190:193], v[182:185], v[50:65]
	s_waitcnt vmcnt(9)
	v_mfma_f32_32x32x16_bf16 v[34:49], v[178:181], v[182:185], v[34:49]
	s_waitcnt vmcnt(7)
	v_mfma_f32_32x32x16_bf16 v[50:65], v[202:205], v[198:201], v[50:65]
	s_waitcnt vmcnt(6)
	v_mfma_f32_32x32x16_bf16 v[34:49], v[194:197], v[198:201], v[34:49]
	s_waitcnt vmcnt(4)
	v_mfma_f32_32x32x16_bf16 v[50:65], v[100:103], v[96:99], v[50:65]
	s_waitcnt vmcnt(3)
	v_mfma_f32_32x32x16_bf16 v[34:49], v[206:209], v[96:99], v[34:49]
	s_waitcnt vmcnt(1)
	v_mfma_f32_32x32x16_bf16 v[50:65], v[112:115], v[108:111], v[50:65]
	s_waitcnt vmcnt(0)
	v_mfma_f32_32x32x16_bf16 v[34:49], v[104:107], v[108:111], v[34:49]
	v_lshl_or_b32 v82, s24, 5, v1
	v_cmp_gt_i32_e32 vcc, s45, v82
	s_and_saveexec_b64 s[24:25], vcc
	s_cbranch_execz .Lh_963
; #define GAS __attribute__((address_space(1)))
; __device__ __forceinline__ unsigned pk2(float lo, float hi) { const f32x2cv v = {lo, hi}; return __builtin_bit_cast(unsigned, __builtin_convertvector(v, bf16x2cv)); }
; __device__ __forceinline__ float gelu_tanh(float x) { const float u = 0.7978845608028654f * (x + 0.044715f * x * x * x); return x * __builtin_amdgcn_rcpf(1.0f + __builtin_amdgcn_exp2f(-2.8853900817779268f * u)); }
; __device__ __forceinline__ void ph_s5_out(Frame& F) {
;     ...
;         if (valid) {
;             const float* dsk = inp(F, 24) + 16 * g;
; #pragma unroll
;             for (int i = 0; i < 4; ++i)
; #pragma unroll
;                 for (int k = 0; k < 4; ++k) { const int tloc = 2 * (wave + 8 * i) + (k >> 1), p0 = 8 * (k & 1) + 4 * hh; const size_t m = (size_t)chunk * 64 + tloc;
;                     const v2u uw = *(const GAS v2u*)((chunk < 256 ? (const bf16*)(ws + WS_UG) : (const bf16*)(ws + WS_UGC)) + ug_index(g, (int)m, p0));
;                     const float y0 = gelu_tanh(acc[i][4 * k] + dsk[p0] * bflo(uw.x)), y1 = gelu_tanh(acc[i][4 * k + 1] + dsk[p0 + 1] * bfhi(uw.x));
;                     const float y2 = gelu_tanh(acc[i][4 * k + 2] + dsk[p0 + 2] * bflo(uw.y)), y3 = gelu_tanh(acc[i][4 * k + 3] + dsk[p0 + 3] * bfhi(uw.y));
;                     v2u zw; zw.x = pk2(y0, y1); zw.y = pk2(y2, y3);
;                     *(GAS v2u*)((bf16*)(ws + WS_Z) + m * 512 + 16 * g + p0) = zw; }
	v_mov_b32_e32 v68, s46
	ds_read_b64 v[84:85], v68
	v_ashrrev_i32_e32 v83, 31, v82
	v_lshlrev_b64 v[88:89], 6, v[82:83]
	v_cmp_gt_i32_e32 vcc, s47, v82
	v_lshl_add_u64 v[102:103], v[88:89], 0, s[4:5]
	v_ashrrev_i32_e32 v83, 11, v102
	v_cndmask_b32_e32 v68, v94, v95, vcc
	v_lshl_add_u64 v[86:87], v[70:71], 0, v[68:69]
	v_ashrrev_i32_e32 v68, 6, v102
	v_add_u32_e32 v83, s30, v83
	v_mov_b32_e32 v96, s26
	v_cmp_gt_i32_e32 vcc, s47, v68
	s_lshl_b32 s28, s26, 4
	s_waitcnt lgkmcnt(0)
	v_readfirstlane_b32 s27, v84
	v_and_b32_e32 v97, 31, v68
	v_cndmask_b32_e32 v84, v96, v83, vcc
	s_ashr_i32 s29, s28, 31
	v_readfirstlane_b32 s31, v85
	v_or_b32_e32 v82, v97, v67
	v_ashrrev_i32_e32 v85, 31, v84
	v_lshlrev_b32_e32 v68, 6, v102
	s_lshl_b64 s[34:35], s[28:29], 2
	v_and_b32_e32 v68, 0xf80, v68
	v_ashrrev_i32_e32 v83, 31, v82
	v_lshlrev_b64 v[84:85], 16, v[84:85]
	v_lshl_add_u64 v[82:83], v[68:69], 0, v[82:83]
	v_lshl_add_u64 v[104:105], v[86:87], 0, v[84:85]
	s_add_u32 s26, s27, s34
	v_lshl_add_u64 v[82:83], v[82:83], 4, v[104:105]
	s_addc_u32 s27, s31, s35
	v_lshl_add_u64 v[98:99], v[188:189], 2, s[26:27]
	global_load_dwordx4 v[174:177], v[98:99], off
	global_load_dwordx4 v[178:181], v[98:99], off offset:32
	global_load_dwordx2 v[142:143], v[82:83], off
	global_load_dwordx2 v[144:145], v[82:83], off offset:512
	global_load_dwordx2 v[146:147], v[82:83], off offset:1024
	global_load_dwordx2 v[148:149], v[82:83], off offset:1536
	v_lshl_add_u64 v[82:83], v[82:83], 0, s[22:23]
	global_load_dwordx2 v[150:151], v[82:83], off
	global_load_dwordx2 v[152:153], v[82:83], off offset:512
	global_load_dwordx2 v[154:155], v[82:83], off offset:1024
	global_load_dwordx2 v[156:157], v[82:83], off offset:1536
	s_lshl_b64 s[26:27], s[28:29], 1
	s_add_u32 s26, s38, s26
	v_lshlrev_b64 v[102:103], 10, v[102:103]
	s_addc_u32 s27, s39, s27
	v_lshlrev_b64 v[84:85], 1, v[188:189]
	v_lshl_add_u64 v[102:103], s[26:27], 0, v[102:103]
	v_lshl_add_u64 v[102:103], v[102:103], 0, v[84:85]
	s_waitcnt vmcnt(7)
	v_lshlrev_b32_e32 v182, 16, v142
	v_and_b32_e32 v183, 0xffff0000, v142
	v_lshlrev_b32_e32 v184, 16, v143
	v_and_b32_e32 v185, 0xffff0000, v143
	v_pk_fma_f32 v[194:195], v[174:175], v[182:183], v[50:51]
	v_pk_fma_f32 v[196:197], v[176:177], v[184:185], v[52:53]
	v_mul_f32_e32 v190, 0x3d372713, v194
	v_mul_f32_e32 v191, 0x3d372713, v195
	v_mul_f32_e32 v192, 0x3d372713, v196
	v_mul_f32_e32 v193, 0x3d372713, v197
	v_mul_f32_e32 v190, v194, v190
	v_mul_f32_e32 v191, v195, v191
	v_mul_f32_e32 v192, v196, v192
	v_mul_f32_e32 v193, v197, v193
	v_fma_f32 v190, v194, v190, v194
	v_fma_f32 v191, v195, v191, v195
	v_fma_f32 v192, v196, v192, v196
	v_fma_f32 v193, v197, v193, v197
	v_mul_f32_e32 v190, 0x3f4c422a, v190
	v_mul_f32_e32 v191, 0x3f4c422a, v191
	v_mul_f32_e32 v192, 0x3f4c422a, v192
	v_mul_f32_e32 v193, 0x3f4c422a, v193
	v_mul_f32_e32 v190, 0xc038aa3b, v190
	v_mul_f32_e32 v191, 0xc038aa3b, v191
	v_mul_f32_e32 v192, 0xc038aa3b, v192
	v_mul_f32_e32 v193, 0xc038aa3b, v193
	v_exp_f32_e32 v190, v190
	v_exp_f32_e32 v191, v191
	v_exp_f32_e32 v192, v192
	v_exp_f32_e32 v193, v193
	v_add_f32_e32 v190, 1.0, v190
	v_add_f32_e32 v191, 1.0, v191
	v_add_f32_e32 v192, 1.0, v192
	v_add_f32_e32 v193, 1.0, v193
	v_rcp_f32_e32 v190, v190
	v_rcp_f32_e32 v191, v191
	v_rcp_f32_e32 v192, v192
	v_rcp_f32_e32 v193, v193
	v_pk_mul_f32 v[194:195], v[194:195], v[190:191]
	v_pk_mul_f32 v[196:197], v[196:197], v[192:193]
	v_cvt_pk_bf16_f32 v194, v194, v195
	v_cvt_pk_bf16_f32 v195, v196, v197
	global_store_dwordx2 v[102:103], v[194:195], off
	s_waitcnt vmcnt(7)
	v_lshlrev_b32_e32 v182, 16, v144
	v_and_b32_e32 v183, 0xffff0000, v144
	v_lshlrev_b32_e32 v184, 16, v145
	v_and_b32_e32 v185, 0xffff0000, v145
	v_pk_fma_f32 v[194:195], v[178:179], v[182:183], v[54:55]
	v_pk_fma_f32 v[196:197], v[180:181], v[184:185], v[56:57]
	v_mul_f32_e32 v190, 0x3d372713, v194
	v_mul_f32_e32 v191, 0x3d372713, v195
	v_mul_f32_e32 v192, 0x3d372713, v196
	v_mul_f32_e32 v193, 0x3d372713, v197
	v_mul_f32_e32 v190, v194, v190
	v_mul_f32_e32 v191, v195, v191
	v_mul_f32_e32 v192, v196, v192
	v_mul_f32_e32 v193, v197, v193
	v_fma_f32 v190, v194, v190, v194
	v_fma_f32 v191, v195, v191, v195
	v_fma_f32 v192, v196, v192, v196
	v_fma_f32 v193, v197, v193, v197
	v_mul_f32_e32 v190, 0x3f4c422a, v190
	v_mul_f32_e32 v191, 0x3f4c422a, v191
	v_mul_f32_e32 v192, 0x3f4c422a, v192
	v_mul_f32_e32 v193, 0x3f4c422a, v193
	v_mul_f32_e32 v190, 0xc038aa3b, v190
	v_mul_f32_e32 v191, 0xc038aa3b, v191
	v_mul_f32_e32 v192, 0xc038aa3b, v192
	v_mul_f32_e32 v193, 0xc038aa3b, v193
	v_exp_f32_e32 v190, v190
	v_exp_f32_e32 v191, v191
	v_exp_f32_e32 v192, v192
	v_exp_f32_e32 v193, v193
	v_add_f32_e32 v190, 1.0, v190
	v_add_f32_e32 v191, 1.0, v191
	v_add_f32_e32 v192, 1.0, v192
	v_add_f32_e32 v193, 1.0, v193
	v_rcp_f32_e32 v190, v190
	v_rcp_f32_e32 v191, v191
	v_rcp_f32_e32 v192, v192
	v_rcp_f32_e32 v193, v193
	v_pk_mul_f32 v[194:195], v[194:195], v[190:191]
	v_pk_mul_f32 v[196:197], v[196:197], v[192:193]
	v_cvt_pk_bf16_f32 v194, v194, v195
	v_cvt_pk_bf16_f32 v195, v196, v197
	global_store_dwordx2 v[102:103], v[194:195], off offset:16
	s_waitcnt vmcnt(7)
; #define GAS __attribute__((address_space(1)))
; __device__ __forceinline__ unsigned pk2(float lo, float hi) { const f32x2cv v = {lo, hi}; return __builtin_bit_cast(unsigned, __builtin_convertvector(v, bf16x2cv)); }
; __device__ __forceinline__ float gelu_tanh(float x) { const float u = 0.7978845608028654f * (x + 0.044715f * x * x * x); return x * __builtin_amdgcn_rcpf(1.0f + __builtin_amdgcn_exp2f(-2.8853900817779268f * u)); }
; __device__ __forceinline__ void ph_s5_out(Frame& F) {
;     ...
;                 for (int k = 0; k < 4; ++k) { const int tloc = 2 * (wave + 8 * i) + (k >> 1), p0 = 8 * (k & 1) + 4 * hh; const size_t m = (size_t)chunk * 64 + tloc;
;                     const v2u uw = *(const GAS v2u*)((chunk < 256 ? (const bf16*)(ws + WS_UG) : (const bf16*)(ws + WS_UGC)) + ug_index(g, (int)m, p0));
;                     const float y0 = gelu_tanh(acc[i][4 * k] + dsk[p0] * bflo(uw.x)), y1 = gelu_tanh(acc[i][4 * k + 1] + dsk[p0 + 1] * bfhi(uw.x));
;                     const float y2 = gelu_tanh(acc[i][4 * k + 2] + dsk[p0 + 2] * bflo(uw.y)), y3 = gelu_tanh(acc[i][4 * k + 3] + dsk[p0 + 3] * bfhi(uw.y));
;                     v2u zw; zw.x = pk2(y0, y1); zw.y = pk2(y2, y3);
;                     *(GAS v2u*)((bf16*)(ws + WS_Z) + m * 512 + 16 * g + p0) = zw; }
	v_lshlrev_b32_e32 v182, 16, v146
	v_and_b32_e32 v183, 0xffff0000, v146
	v_lshlrev_b32_e32 v184, 16, v147
	v_and_b32_e32 v185, 0xffff0000, v147
	v_pk_fma_f32 v[194:195], v[174:175], v[182:183], v[58:59]
	v_pk_fma_f32 v[196:197], v[176:177], v[184:185], v[60:61]
	v_mul_f32_e32 v190, 0x3d372713, v194
	v_mul_f32_e32 v191, 0x3d372713, v195
	v_mul_f32_e32 v192, 0x3d372713, v196
	v_mul_f32_e32 v193, 0x3d372713, v197
	v_mul_f32_e32 v190, v194, v190
	v_mul_f32_e32 v191, v195, v191
	v_mul_f32_e32 v192, v196, v192
	v_mul_f32_e32 v193, v197, v193
	v_fma_f32 v190, v194, v190, v194
	v_fma_f32 v191, v195, v191, v195
	v_fma_f32 v192, v196, v192, v196
	v_fma_f32 v193, v197, v193, v197
	v_mul_f32_e32 v190, 0x3f4c422a, v190
	v_mul_f32_e32 v191, 0x3f4c422a, v191
	v_mul_f32_e32 v192, 0x3f4c422a, v192
	v_mul_f32_e32 v193, 0x3f4c422a, v193
	v_mul_f32_e32 v190, 0xc038aa3b, v190
	v_mul_f32_e32 v191, 0xc038aa3b, v191
	v_mul_f32_e32 v192, 0xc038aa3b, v192
	v_mul_f32_e32 v193, 0xc038aa3b, v193
	v_exp_f32_e32 v190, v190
	v_exp_f32_e32 v191, v191
	v_exp_f32_e32 v192, v192
	v_exp_f32_e32 v193, v193
	v_add_f32_e32 v190, 1.0, v190
	v_add_f32_e32 v191, 1.0, v191
	v_add_f32_e32 v192, 1.0, v192
	v_add_f32_e32 v193, 1.0, v193
	v_rcp_f32_e32 v190, v190
	v_rcp_f32_e32 v191, v191
	v_rcp_f32_e32 v192, v192
	v_rcp_f32_e32 v193, v193
	v_pk_mul_f32 v[194:195], v[194:195], v[190:191]
	v_pk_mul_f32 v[196:197], v[196:197], v[192:193]
	v_cvt_pk_bf16_f32 v194, v194, v195
	v_cvt_pk_bf16_f32 v195, v196, v197
	global_store_dwordx2 v[102:103], v[194:195], off offset:1024
	s_waitcnt vmcnt(7)
	v_lshlrev_b32_e32 v182, 16, v148
	v_and_b32_e32 v183, 0xffff0000, v148
	v_lshlrev_b32_e32 v184, 16, v149
	v_and_b32_e32 v185, 0xffff0000, v149
	v_pk_fma_f32 v[194:195], v[178:179], v[182:183], v[62:63]
	v_pk_fma_f32 v[196:197], v[180:181], v[184:185], v[64:65]
	v_mul_f32_e32 v190, 0x3d372713, v194
	v_mul_f32_e32 v191, 0x3d372713, v195
	v_mul_f32_e32 v192, 0x3d372713, v196
	v_mul_f32_e32 v193, 0x3d372713, v197
	v_mul_f32_e32 v190, v194, v190
	v_mul_f32_e32 v191, v195, v191
	v_mul_f32_e32 v192, v196, v192
	v_mul_f32_e32 v193, v197, v193
	v_fma_f32 v190, v194, v190, v194
	v_fma_f32 v191, v195, v191, v195
	v_fma_f32 v192, v196, v192, v196
	v_fma_f32 v193, v197, v193, v197
	v_mul_f32_e32 v190, 0x3f4c422a, v190
	v_mul_f32_e32 v191, 0x3f4c422a, v191
	v_mul_f32_e32 v192, 0x3f4c422a, v192
	v_mul_f32_e32 v193, 0x3f4c422a, v193
	v_mul_f32_e32 v190, 0xc038aa3b, v190
	v_mul_f32_e32 v191, 0xc038aa3b, v191
	v_mul_f32_e32 v192, 0xc038aa3b, v192
	v_mul_f32_e32 v193, 0xc038aa3b, v193
	v_exp_f32_e32 v190, v190
	v_exp_f32_e32 v191, v191
	v_exp_f32_e32 v192, v192
	v_exp_f32_e32 v193, v193
	v_add_f32_e32 v190, 1.0, v190
	v_add_f32_e32 v191, 1.0, v191
	v_add_f32_e32 v192, 1.0, v192
	v_add_f32_e32 v193, 1.0, v193
	v_rcp_f32_e32 v190, v190
	v_rcp_f32_e32 v191, v191
	v_rcp_f32_e32 v192, v192
	v_rcp_f32_e32 v193, v193
	v_pk_mul_f32 v[194:195], v[194:195], v[190:191]
	v_pk_mul_f32 v[196:197], v[196:197], v[192:193]
	v_cvt_pk_bf16_f32 v194, v194, v195
	v_cvt_pk_bf16_f32 v195, v196, v197
	global_store_dwordx2 v[102:103], v[194:195], off offset:1040
	v_lshl_add_u64 v[102:103], v[102:103], 0, s[22:23]
	s_waitcnt vmcnt(7)
	v_lshlrev_b32_e32 v182, 16, v150
	v_and_b32_e32 v183, 0xffff0000, v150
	v_lshlrev_b32_e32 v184, 16, v151
	v_and_b32_e32 v185, 0xffff0000, v151
	v_pk_fma_f32 v[194:195], v[174:175], v[182:183], v[34:35]
	v_pk_fma_f32 v[196:197], v[176:177], v[184:185], v[36:37]
	v_mul_f32_e32 v190, 0x3d372713, v194
	v_mul_f32_e32 v191, 0x3d372713, v195
	v_mul_f32_e32 v192, 0x3d372713, v196
	v_mul_f32_e32 v193, 0x3d372713, v197
	v_mul_f32_e32 v190, v194, v190
	v_mul_f32_e32 v191, v195, v191
	v_mul_f32_e32 v192, v196, v192
	v_mul_f32_e32 v193, v197, v193
	v_fma_f32 v190, v194, v190, v194
	v_fma_f32 v191, v195, v191, v195
	v_fma_f32 v192, v196, v192, v196
	v_fma_f32 v193, v197, v193, v197
	v_mul_f32_e32 v190, 0x3f4c422a, v190
	v_mul_f32_e32 v191, 0x3f4c422a, v191
	v_mul_f32_e32 v192, 0x3f4c422a, v192
	v_mul_f32_e32 v193, 0x3f4c422a, v193
	v_mul_f32_e32 v190, 0xc038aa3b, v190
	v_mul_f32_e32 v191, 0xc038aa3b, v191
	v_mul_f32_e32 v192, 0xc038aa3b, v192
	v_mul_f32_e32 v193, 0xc038aa3b, v193
	v_exp_f32_e32 v190, v190
	v_exp_f32_e32 v191, v191
	v_exp_f32_e32 v192, v192
	v_exp_f32_e32 v193, v193
	v_add_f32_e32 v190, 1.0, v190
	v_add_f32_e32 v191, 1.0, v191
	v_add_f32_e32 v192, 1.0, v192
	v_add_f32_e32 v193, 1.0, v193
	v_rcp_f32_e32 v190, v190
	v_rcp_f32_e32 v191, v191
	v_rcp_f32_e32 v192, v192
	v_rcp_f32_e32 v193, v193
	v_pk_mul_f32 v[194:195], v[194:195], v[190:191]
	v_pk_mul_f32 v[196:197], v[196:197], v[192:193]
	v_cvt_pk_bf16_f32 v194, v194, v195
	v_cvt_pk_bf16_f32 v195, v196, v197
	global_store_dwordx2 v[102:103], v[194:195], off
	s_waitcnt vmcnt(7)
; #define GAS __attribute__((address_space(1)))
; __device__ __forceinline__ unsigned pk2(float lo, float hi) { const f32x2cv v = {lo, hi}; return __builtin_bit_cast(unsigned, __builtin_convertvector(v, bf16x2cv)); }
; __device__ __forceinline__ float gelu_tanh(float x) { const float u = 0.7978845608028654f * (x + 0.044715f * x * x * x); return x * __builtin_amdgcn_rcpf(1.0f + __builtin_amdgcn_exp2f(-2.8853900817779268f * u)); }
; __device__ __forceinline__ void ph_s5_out(Frame& F) {
;     ...
;         if (valid) {
;             const float* dsk = inp(F, 24) + 16 * g;
; #pragma unroll
;             for (int i = 0; i < 4; ++i)
; #pragma unroll
;                 for (int k = 0; k < 4; ++k) { const int tloc = 2 * (wave + 8 * i) + (k >> 1), p0 = 8 * (k & 1) + 4 * hh; const size_t m = (size_t)chunk * 64 + tloc;
;                     const v2u uw = *(const GAS v2u*)((chunk < 256 ? (const bf16*)(ws + WS_UG) : (const bf16*)(ws + WS_UGC)) + ug_index(g, (int)m, p0));
;                     const float y0 = gelu_tanh(acc[i][4 * k] + dsk[p0] * bflo(uw.x)), y1 = gelu_tanh(acc[i][4 * k + 1] + dsk[p0 + 1] * bfhi(uw.x));
;                     const float y2 = gelu_tanh(acc[i][4 * k + 2] + dsk[p0 + 2] * bflo(uw.y)), y3 = gelu_tanh(acc[i][4 * k + 3] + dsk[p0 + 3] * bfhi(uw.y));
;                     v2u zw; zw.x = pk2(y0, y1); zw.y = pk2(y2, y3);
;                     *(GAS v2u*)((bf16*)(ws + WS_Z) + m * 512 + 16 * g + p0) = zw; }
	v_lshlrev_b32_e32 v182, 16, v152
	v_and_b32_e32 v183, 0xffff0000, v152
	v_lshlrev_b32_e32 v184, 16, v153
	v_and_b32_e32 v185, 0xffff0000, v153
	v_pk_fma_f32 v[194:195], v[178:179], v[182:183], v[38:39]
	v_pk_fma_f32 v[196:197], v[180:181], v[184:185], v[40:41]
	v_mul_f32_e32 v190, 0x3d372713, v194
	v_mul_f32_e32 v191, 0x3d372713, v195
	v_mul_f32_e32 v192, 0x3d372713, v196
	v_mul_f32_e32 v193, 0x3d372713, v197
	v_mul_f32_e32 v190, v194, v190
	v_mul_f32_e32 v191, v195, v191
	v_mul_f32_e32 v192, v196, v192
	v_mul_f32_e32 v193, v197, v193
	v_fma_f32 v190, v194, v190, v194
	v_fma_f32 v191, v195, v191, v195
	v_fma_f32 v192, v196, v192, v196
	v_fma_f32 v193, v197, v193, v197
	v_mul_f32_e32 v190, 0x3f4c422a, v190
	v_mul_f32_e32 v191, 0x3f4c422a, v191
	v_mul_f32_e32 v192, 0x3f4c422a, v192
	v_mul_f32_e32 v193, 0x3f4c422a, v193
	v_mul_f32_e32 v190, 0xc038aa3b, v190
	v_mul_f32_e32 v191, 0xc038aa3b, v191
	v_mul_f32_e32 v192, 0xc038aa3b, v192
	v_mul_f32_e32 v193, 0xc038aa3b, v193
	v_exp_f32_e32 v190, v190
	v_exp_f32_e32 v191, v191
	v_exp_f32_e32 v192, v192
	v_exp_f32_e32 v193, v193
	v_add_f32_e32 v190, 1.0, v190
	v_add_f32_e32 v191, 1.0, v191
	v_add_f32_e32 v192, 1.0, v192
	v_add_f32_e32 v193, 1.0, v193
	v_rcp_f32_e32 v190, v190
	v_rcp_f32_e32 v191, v191
	v_rcp_f32_e32 v192, v192
	v_rcp_f32_e32 v193, v193
	v_pk_mul_f32 v[194:195], v[194:195], v[190:191]
	v_pk_mul_f32 v[196:197], v[196:197], v[192:193]
	v_cvt_pk_bf16_f32 v194, v194, v195
	v_cvt_pk_bf16_f32 v195, v196, v197
	global_store_dwordx2 v[102:103], v[194:195], off offset:16
	s_waitcnt vmcnt(7)
	v_lshlrev_b32_e32 v182, 16, v154
	v_and_b32_e32 v183, 0xffff0000, v154
	v_lshlrev_b32_e32 v184, 16, v155
	v_and_b32_e32 v185, 0xffff0000, v155
	v_pk_fma_f32 v[194:195], v[174:175], v[182:183], v[42:43]
	v_pk_fma_f32 v[196:197], v[176:177], v[184:185], v[44:45]
	v_mul_f32_e32 v190, 0x3d372713, v194
	v_mul_f32_e32 v191, 0x3d372713, v195
	v_mul_f32_e32 v192, 0x3d372713, v196
	v_mul_f32_e32 v193, 0x3d372713, v197
	v_mul_f32_e32 v190, v194, v190
	v_mul_f32_e32 v191, v195, v191
	v_mul_f32_e32 v192, v196, v192
	v_mul_f32_e32 v193, v197, v193
	v_fma_f32 v190, v194, v190, v194
	v_fma_f32 v191, v195, v191, v195
	v_fma_f32 v192, v196, v192, v196
	v_fma_f32 v193, v197, v193, v197
	v_mul_f32_e32 v190, 0x3f4c422a, v190
	v_mul_f32_e32 v191, 0x3f4c422a, v191
	v_mul_f32_e32 v192, 0x3f4c422a, v192
	v_mul_f32_e32 v193, 0x3f4c422a, v193
	v_mul_f32_e32 v190, 0xc038aa3b, v190
	v_mul_f32_e32 v191, 0xc038aa3b, v191
	v_mul_f32_e32 v192, 0xc038aa3b, v192
	v_mul_f32_e32 v193, 0xc038aa3b, v193
	v_exp_f32_e32 v190, v190
	v_exp_f32_e32 v191, v191
	v_exp_f32_e32 v192, v192
	v_exp_f32_e32 v193, v193
	v_add_f32_e32 v190, 1.0, v190
	v_add_f32_e32 v191, 1.0, v191
	v_add_f32_e32 v192, 1.0, v192
	v_add_f32_e32 v193, 1.0, v193
	v_rcp_f32_e32 v190, v190
	v_rcp_f32_e32 v191, v191
	v_rcp_f32_e32 v192, v192
	v_rcp_f32_e32 v193, v193
	v_pk_mul_f32 v[194:195], v[194:195], v[190:191]
	v_pk_mul_f32 v[196:197], v[196:197], v[192:193]
	v_cvt_pk_bf16_f32 v194, v194, v195
	v_cvt_pk_bf16_f32 v195, v196, v197
	global_store_dwordx2 v[102:103], v[194:195], off offset:1024
	s_waitcnt vmcnt(7)
	v_lshlrev_b32_e32 v182, 16, v156
	v_and_b32_e32 v183, 0xffff0000, v156
	v_lshlrev_b32_e32 v184, 16, v157
	v_and_b32_e32 v185, 0xffff0000, v157
	v_pk_fma_f32 v[194:195], v[178:179], v[182:183], v[46:47]
	v_pk_fma_f32 v[196:197], v[180:181], v[184:185], v[48:49]
	v_mul_f32_e32 v190, 0x3d372713, v194
	v_mul_f32_e32 v191, 0x3d372713, v195
	v_mul_f32_e32 v192, 0x3d372713, v196
	v_mul_f32_e32 v193, 0x3d372713, v197
	v_mul_f32_e32 v190, v194, v190
	v_mul_f32_e32 v191, v195, v191
	v_mul_f32_e32 v192, v196, v192
	v_mul_f32_e32 v193, v197, v193
	v_fma_f32 v190, v194, v190, v194
	v_fma_f32 v191, v195, v191, v195
	v_fma_f32 v192, v196, v192, v196
	v_fma_f32 v193, v197, v193, v197
	v_mul_f32_e32 v190, 0x3f4c422a, v190
	v_mul_f32_e32 v191, 0x3f4c422a, v191
	v_mul_f32_e32 v192, 0x3f4c422a, v192
	v_mul_f32_e32 v193, 0x3f4c422a, v193
	v_mul_f32_e32 v190, 0xc038aa3b, v190
	v_mul_f32_e32 v191, 0xc038aa3b, v191
	v_mul_f32_e32 v192, 0xc038aa3b, v192
	v_mul_f32_e32 v193, 0xc038aa3b, v193
	v_exp_f32_e32 v190, v190
	v_exp_f32_e32 v191, v191
	v_exp_f32_e32 v192, v192
	v_exp_f32_e32 v193, v193
	v_add_f32_e32 v190, 1.0, v190
	v_add_f32_e32 v191, 1.0, v191
	v_add_f32_e32 v192, 1.0, v192
	v_add_f32_e32 v193, 1.0, v193
	v_rcp_f32_e32 v190, v190
	v_rcp_f32_e32 v191, v191
	v_rcp_f32_e32 v192, v192
	v_rcp_f32_e32 v193, v193
	v_pk_mul_f32 v[194:195], v[194:195], v[190:191]
	v_pk_mul_f32 v[196:197], v[196:197], v[192:193]
	v_cvt_pk_bf16_f32 v194, v194, v195
	v_cvt_pk_bf16_f32 v195, v196, v197
	global_store_dwordx2 v[102:103], v[194:195], off offset:1040
	s_branch .Lh_963
